# v117 + lane-group reductions via DPP adds (gdn prep, scan) + scan: first fragment reads issued ahead of the state repack converts
# baseline (speedup 1.0000x reference)
.LBB0_444:
	s_add_i32 s16, s16, 1
	s_waitcnt lgkmcnt(0)
	s_barrier
	s_add_u32 s12, s12, 4
	s_addc_u32 s13, s13, 0
	s_mov_b64 s[8:9], 0x170000
	v_lshl_add_u64 v[134:135], v[134:135], 0, s[38:39]
	s_cmp_lg_u32 s16, 64
	v_lshl_add_u64 v[136:137], v[136:137], 0, s[8:9]
	s_cbranch_scc0 .LBB0_449

.LBB0_447:
	ds_read_b128 v[110:113], v164 offset:17408
	ds_read_b128 v[114:117], v164 offset:17472
	ds_read_b128 v[144:147], v164 offset:17536
	ds_read_b128 v[148:151], v164 offset:17600
	ds_read_b128 v[152:155], v164 offset:21760
	ds_read_b128 v[170:173], v164 offset:21824
	ds_read_b128 v[174:177], v164 offset:21888
	ds_read_b128 v[178:181], v164 offset:21952
	v_cvt_pk_bf16_f32 v94, v62, v63
	v_cvt_pk_bf16_f32 v95, v64, v65
	v_cvt_pk_bf16_f32 v96, v66, v67
	v_cvt_pk_bf16_f32 v97, v68, v69
	v_cvt_pk_bf16_f32 v98, v74, v75
	v_cvt_pk_bf16_f32 v99, v76, v77
	v_cvt_pk_bf16_f32 v100, v70, v71
	v_cvt_pk_bf16_f32 v101, v72, v73
	v_cvt_pk_bf16_f32 v102, v78, v79
	v_cvt_pk_bf16_f32 v103, v80, v81
	v_cvt_pk_bf16_f32 v104, v82, v83
	v_cvt_pk_bf16_f32 v105, v84, v85
	v_cvt_pk_bf16_f32 v106, v86, v87
	v_cvt_pk_bf16_f32 v107, v88, v89
	v_cvt_pk_bf16_f32 v108, v90, v91
	v_cvt_pk_bf16_f32 v109, v92, v93
	s_waitcnt lgkmcnt(7)
	v_mfma_f32_16x16x32_bf16 v[110:113], v[110:113], v[94:97], 0
	s_waitcnt lgkmcnt(6)
	v_mfma_f32_16x16x32_bf16 v[110:113], v[114:117], v[98:101], v[110:113]
	s_waitcnt lgkmcnt(5)
	v_mfma_f32_16x16x32_bf16 v[110:113], v[144:147], v[102:105], v[110:113]
	s_waitcnt lgkmcnt(4)
	v_mfma_f32_16x16x32_bf16 v[110:113], v[148:151], v[106:109], v[110:113]
	ds_read_b128 v[114:117], v164 offset:26112
	ds_read_b128 v[144:147], v164 offset:26176
	ds_read_b128 v[148:151], v164 offset:26240
	ds_read_b128 v[182:185], v164 offset:26304
	s_cmp_eq_u32 s16, 63
	s_cbranch_scc1 .Lscan_noload
	s_add_i32 s30, s17, s16
	s_lshl_b64 s[34:35], s[30:31], 13
	s_lshl_b64 s[36:37], s[30:31], 14
	s_add_u32 s40, s22, s36
	s_addc_u32 s41, s23, s37
	v_lshl_add_u64 v[2:3], s[40:41], 0, v[138:139]
	v_lshl_add_u64 v[6:7], s[40:41], 0, v[140:141]
	s_add_u32 s40, s28, s36
	s_addc_u32 s41, s29, s37
	v_lshl_add_u64 v[18:19], v[128:129], 0, s[34:35]
	s_add_u32 s34, s24, s36
	s_addc_u32 s35, s25, s37
	v_lshl_add_u64 v[22:23], s[34:35], 0, v[138:139]
	v_lshl_add_u64 v[26:27], s[34:35], 0, v[140:141]
	s_lshl_b64 s[34:35], s[30:31], 15
	s_add_u32 s34, s26, s34
	s_addc_u32 s35, s27, s35
	v_lshl_add_u64 v[30:31], s[34:35], 0, v[120:121]
	v_lshl_add_u64 v[34:35], s[34:35], 0, v[122:123]
	v_lshl_add_u64 v[38:39], s[34:35], 0, v[124:125]
	v_lshl_add_u64 v[42:43], s[34:35], 0, v[126:127]
	s_add_u32 s34, s12, s6
	v_lshl_add_u64 v[10:11], s[40:41], 0, v[138:139]
	v_lshl_add_u64 v[14:15], s[40:41], 0, v[140:141]
	s_addc_u32 s35, s13, 0
	global_load_dwordx4 v[2:5], v[2:3], off
	s_nop 0
	global_load_dwordx4 v[6:9], v[6:7], off
	s_nop 0
	global_load_dwordx4 v[10:13], v[10:11], off
	s_nop 0
	global_load_dwordx4 v[14:17], v[14:15], off
	s_nop 0
	global_load_dwordx4 v[18:21], v[18:19], off
	s_nop 0
	global_load_dwordx4 v[22:25], v[22:23], off
	s_nop 0
	global_load_dwordx4 v[26:29], v[26:27], off
	s_nop 0
	global_load_dwordx4 v[30:33], v[30:31], off
	s_nop 0
	global_load_dwordx4 v[34:37], v[34:35], off
	s_nop 0
	global_load_dwordx4 v[38:41], v[38:39], off
	v_lshl_add_u64 v[54:55], v[136:137], 0, s[6:7]
	global_load_dword v162, v131, s[34:35]
	s_mov_b64 s[34:35], 0x48675000
	v_lshl_add_u64 v[56:57], v[54:55], 0, s[34:35]
	v_add_co_u32_e32 v54, vcc, 0x48675000, v54
	global_load_dwordx4 v[42:45], v[42:43], off
	s_nop 0
	v_addc_co_u32_e32 v55, vcc, 0, v55, vcc
	global_load_dwordx4 v[58:61], v[54:55], off
	s_nop 0
	global_load_dwordx4 v[54:57], v[56:57], off offset:16
.Lscan_noload:
	s_waitcnt lgkmcnt(7)
	v_mfma_f32_16x16x32_bf16 v[152:155], v[152:155], v[94:97], 0
	s_waitcnt lgkmcnt(6)
	v_mfma_f32_16x16x32_bf16 v[152:155], v[170:173], v[98:101], v[152:155]
	s_waitcnt lgkmcnt(5)
	v_mfma_f32_16x16x32_bf16 v[152:155], v[174:177], v[102:105], v[152:155]
	s_waitcnt lgkmcnt(4)
	v_mfma_f32_16x16x32_bf16 v[152:155], v[178:181], v[106:109], v[152:155]
	ds_read_b128 v[170:173], v164 offset:30464
	ds_read_b128 v[174:177], v164 offset:30528
	ds_read_b128 v[178:181], v164 offset:30592
	ds_read_b128 v[186:189], v164 offset:30656
	s_waitcnt lgkmcnt(7)
	v_mfma_f32_16x16x32_bf16 v[114:117], v[114:117], v[94:97], 0
	s_waitcnt lgkmcnt(6)
	v_mfma_f32_16x16x32_bf16 v[114:117], v[144:147], v[98:101], v[114:117]
	s_waitcnt lgkmcnt(5)
	v_mfma_f32_16x16x32_bf16 v[114:117], v[148:151], v[102:105], v[114:117]
	s_waitcnt lgkmcnt(4)
	v_mfma_f32_16x16x32_bf16 v[114:117], v[182:185], v[106:109], v[114:117]
	ds_read_b128 v[144:147], v164
	ds_read_b128 v[148:151], v164 offset:64
	ds_read_b128 v[182:185], v164 offset:128
	ds_read_b128 v[190:193], v164 offset:192
	s_waitcnt lgkmcnt(7)
	v_mfma_f32_16x16x32_bf16 v[170:173], v[170:173], v[94:97], 0
	s_waitcnt lgkmcnt(6)
	v_mfma_f32_16x16x32_bf16 v[170:173], v[174:177], v[98:101], v[170:173]
	s_waitcnt lgkmcnt(5)
	v_mfma_f32_16x16x32_bf16 v[170:173], v[178:181], v[102:105], v[170:173]
	s_waitcnt lgkmcnt(4)
	v_mfma_f32_16x16x32_bf16 v[170:173], v[186:189], v[106:109], v[170:173]
	ds_read_b128 v[174:177], v164 offset:4352
	ds_read_b128 v[178:181], v164 offset:4416
	ds_read_b128 v[186:189], v164 offset:4480
	ds_read_b128 v[194:197], v164 offset:4544
	v_add_u32_e32 v142, 0x400, v163
	ds_read2_b32 v[198:199], v163 offset1:132
	ds_read2_b32 v[200:201], v142 offset0:8 offset1:140
	s_waitcnt lgkmcnt(0)
	v_mfma_f32_16x16x32_bf16 v[144:147], v[144:147], v[94:97], v[198:201]
	v_mfma_f32_16x16x32_bf16 v[144:147], v[148:151], v[98:101], v[144:147]
	v_mfma_f32_16x16x32_bf16 v[144:147], v[182:185], v[102:105], v[144:147]
	v_mfma_f32_16x16x32_bf16 v[144:147], v[190:193], v[106:109], v[144:147]
	ds_read_b128 v[148:151], v164 offset:8704
	ds_read_b128 v[182:185], v164 offset:8768
	ds_read_b128 v[190:193], v164 offset:8832
	ds_read_b128 v[198:201], v164 offset:8896
	v_add_u32_e32 v142, 0x2000, v163
	ds_read2_b32 v[202:203], v142 offset0:64 offset1:196
	v_add_u32_e32 v142, 0x2400, v163
	ds_read2_b32 v[204:205], v142 offset0:72 offset1:204
	s_waitcnt lgkmcnt(0)
	v_mfma_f32_16x16x32_bf16 v[174:177], v[174:177], v[94:97], v[202:205]
	v_mfma_f32_16x16x32_bf16 v[174:177], v[178:181], v[98:101], v[174:177]
	v_mfma_f32_16x16x32_bf16 v[174:177], v[186:189], v[102:105], v[174:177]
	v_mfma_f32_16x16x32_bf16 v[174:177], v[194:197], v[106:109], v[174:177]
	ds_read_b128 v[178:181], v164 offset:13056
	ds_read_b128 v[186:189], v164 offset:13120
	ds_read_b128 v[194:197], v164 offset:13184
	ds_read_b128 v[202:205], v164 offset:13248
	v_add_u32_e32 v142, 0x4200, v163
	ds_read2_b32 v[206:207], v142 offset1:132
	v_add_u32_e32 v142, 0x4600, v163
	ds_read2_b32 v[208:209], v142 offset0:8 offset1:140
	s_waitcnt lgkmcnt(0)
	v_mfma_f32_16x16x32_bf16 v[148:151], v[148:151], v[94:97], v[206:209]
	v_mfma_f32_16x16x32_bf16 v[148:151], v[182:185], v[98:101], v[148:151]
	v_mfma_f32_16x16x32_bf16 v[148:151], v[190:193], v[102:105], v[148:151]
	v_mfma_f32_16x16x32_bf16 v[148:151], v[198:201], v[106:109], v[148:151]
	ds_read_b128 v[182:185], v165 offset:34816
	ds_read_b128 v[190:193], v165 offset:34880
	ds_read_b128 v[198:201], v165 offset:37120
	ds_read_b128 v[206:209], v165 offset:37184
	v_add_u32_e32 v142, 0x6200, v163
	ds_read2_b32 v[210:211], v142 offset0:64 offset1:196
	v_add_u32_e32 v142, 0x6600, v163
	ds_read2_b32 v[212:213], v142 offset0:72 offset1:204
	s_waitcnt lgkmcnt(0)
	v_mfma_f32_16x16x32_bf16 v[94:97], v[178:181], v[94:97], v[210:213]
	v_mfma_f32_16x16x32_bf16 v[94:97], v[186:189], v[98:101], v[94:97]
	v_mfma_f32_16x16x32_bf16 v[94:97], v[194:197], v[102:105], v[94:97]
	ds_read_b128 v[98:101], v165 offset:39424
	ds_read_b128 v[102:105], v165 offset:39488
	ds_read_b128 v[178:181], v165 offset:41728
	ds_read_b128 v[186:189], v165 offset:41792
	v_mfma_f32_16x16x32_bf16 v[94:97], v[202:205], v[106:109], v[94:97]
	v_cvt_pk_bf16_f32 v106, v144, v145
	v_cvt_pk_bf16_f32 v107, v146, v147
	v_cvt_pk_bf16_f32 v108, v174, v175
	v_cvt_pk_bf16_f32 v109, v176, v177
	v_cvt_pk_bf16_f32 v144, v148, v149
	v_cvt_pk_bf16_f32 v145, v150, v151
	v_mfma_f32_16x16x32_bf16 v[110:113], v[182:185], v[106:109], v[110:113]
	s_nop 0
	v_cvt_pk_bf16_f32 v146, v94, v95
	v_cvt_pk_bf16_f32 v147, v96, v97
	s_nop 1
	v_mfma_f32_16x16x32_bf16 v[94:97], v[190:193], v[144:147], v[110:113]
	v_mfma_f32_16x16x32_bf16 v[110:113], v[198:201], v[106:109], v[152:155]
	ds_read_b128 v[148:151], v165 offset:44032
	s_nop 1
	ds_read_b128 v[152:155], v165 offset:44096
	ds_read_b128 v[174:177], v165 offset:46336
	ds_read_b128 v[182:185], v165 offset:46400
	v_mfma_f32_16x16x32_bf16 v[110:113], v[206:209], v[144:147], v[110:113]
	s_waitcnt lgkmcnt(7)
	v_mfma_f32_16x16x32_bf16 v[98:101], v[98:101], v[106:109], v[114:117]
	s_waitcnt lgkmcnt(6)
	v_mfma_f32_16x16x32_bf16 v[98:101], v[102:105], v[144:147], v[98:101]
	s_waitcnt lgkmcnt(5)
	v_mfma_f32_16x16x32_bf16 v[102:105], v[178:181], v[106:109], v[170:173]
	s_waitcnt lgkmcnt(4)
	v_mfma_f32_16x16x32_bf16 v[102:105], v[186:189], v[144:147], v[102:105]
	ds_read_b128 v[114:117], v165 offset:48640
	ds_read_b128 v[170:173], v165 offset:48704
	ds_read_b128 v[178:181], v165 offset:50944
	ds_read_b128 v[186:189], v165 offset:51008
	v_pk_mul_f32 v[64:65], v[64:65], v[130:131] op_sel_hi:[1,0]
	v_pk_mul_f32 v[62:63], v[62:63], v[130:131] op_sel_hi:[1,0]
	v_pk_mul_f32 v[68:69], v[68:69], v[130:131] op_sel_hi:[1,0]
	v_pk_mul_f32 v[66:67], v[66:67], v[130:131] op_sel_hi:[1,0]
	s_waitcnt lgkmcnt(7)
	v_mfma_f32_16x16x32_bf16 v[62:65], v[148:151], v[106:109], v[62:65]
	v_mul_f32_e64 v76, v76, v130
	v_mul_f32_e64 v77, v77, v130
	v_pk_mul_f32 v[74:75], v[74:75], v[130:131] op_sel_hi:[1,0]
	v_pk_mul_f32 v[72:73], v[72:73], v[130:131] op_sel_hi:[1,0]
	s_waitcnt lgkmcnt(5)
	v_mfma_f32_16x16x32_bf16 v[66:69], v[174:177], v[106:109], v[66:69]
	v_mul_f32_e64 v70, v70, v130
	v_mul_f32_e64 v71, v71, v130
	v_pk_mul_f32 v[80:81], v[80:81], v[130:131] op_sel_hi:[1,0]
	v_pk_mul_f32 v[78:79], v[78:79], v[130:131] op_sel_hi:[1,0]
	v_mfma_f32_16x16x32_bf16 v[62:65], v[152:155], v[144:147], v[62:65]
	v_mul_f32_e64 v84, v84, v130
	v_mul_f32_e64 v85, v85, v130
	v_pk_mul_f32 v[82:83], v[82:83], v[130:131] op_sel_hi:[1,0]
	v_pk_mul_f32 v[88:89], v[88:89], v[130:131] op_sel_hi:[1,0]
	s_waitcnt lgkmcnt(4)
	v_mfma_f32_16x16x32_bf16 v[66:69], v[182:185], v[144:147], v[66:69]
	ds_read_b128 v[148:151], v165 offset:53248
	ds_read_b128 v[152:155], v165 offset:53312
	ds_read_b128 v[174:177], v165 offset:55552
	ds_read_b128 v[182:185], v165 offset:55616
	v_pk_mul_f32 v[86:87], v[86:87], v[130:131] op_sel_hi:[1,0]
	v_pk_mul_f32 v[92:93], v[92:93], v[130:131] op_sel_hi:[1,0]
	v_pk_mul_f32 v[90:91], v[90:91], v[130:131] op_sel_hi:[1,0]
	s_waitcnt lgkmcnt(7)
	v_mfma_f32_16x16x32_bf16 v[74:77], v[114:117], v[106:109], v[74:77]
	s_waitcnt lgkmcnt(5)
	v_mfma_f32_16x16x32_bf16 v[70:73], v[178:181], v[106:109], v[70:73]
	v_mfma_f32_16x16x32_bf16 v[74:77], v[170:173], v[144:147], v[74:77]
	s_waitcnt lgkmcnt(4)
	v_mfma_f32_16x16x32_bf16 v[70:73], v[186:189], v[144:147], v[70:73]
	ds_read_b128 v[114:117], v165 offset:57856
	ds_read_b128 v[170:173], v165 offset:57920
	ds_read_b128 v[178:181], v165 offset:60160
	ds_read_b128 v[186:189], v165 offset:60224
	s_waitcnt lgkmcnt(7)
	v_mfma_f32_16x16x32_bf16 v[78:81], v[148:151], v[106:109], v[78:81]
	s_waitcnt lgkmcnt(5)
	v_mfma_f32_16x16x32_bf16 v[82:85], v[174:177], v[106:109], v[82:85]
	v_mfma_f32_16x16x32_bf16 v[78:81], v[152:155], v[144:147], v[78:81]
	s_waitcnt lgkmcnt(4)
	v_mfma_f32_16x16x32_bf16 v[82:85], v[182:185], v[144:147], v[82:85]
	ds_write2_b32 v167, v94, v95 offset1:132
	v_add_u32_e32 v94, 0xf800, v166
	ds_write2_b32 v94, v96, v97 offset0:8 offset1:140
	v_add_u32_e32 v94, 0x2000, v167
	ds_write2_b32 v94, v110, v111 offset0:64 offset1:196
	v_add_u32_e32 v94, 0x2400, v167
	ds_write2_b32 v94, v112, v113 offset0:72 offset1:204
	v_add_u32_e32 v94, 0x4200, v167
	ds_write2_b32 v94, v98, v99 offset1:132
	v_add_u32_e32 v94, 0x4600, v167
	ds_write2_b32 v94, v100, v101 offset0:8 offset1:140
	v_add_u32_e32 v94, 0x6200, v167
	ds_write2_b32 v94, v102, v103 offset0:64 offset1:196
	v_add_u32_e32 v94, 0x6600, v167
	ds_write2_b32 v94, v104, v105 offset0:72 offset1:204
	s_waitcnt lgkmcnt(0)
	s_barrier
	ds_read_b128 v[110:113], v168 offset:62464
	ds_read_b128 v[102:105], v168 offset:62480
	ds_read_b128 v[98:101], v168 offset:62496
	ds_read_b128 v[94:97], v168 offset:62512
	s_waitcnt lgkmcnt(14)
	v_mfma_f32_16x16x32_bf16 v[86:89], v[114:117], v[106:109], v[86:89]
	v_lshlrev_b32_e32 v150, 16, v46
	v_lshlrev_b32_e32 v151, 16, v47
	s_mov_b32 s30, 0x5f901000
	s_waitcnt lgkmcnt(13)
	v_mfma_f32_16x16x32_bf16 v[90:93], v[178:181], v[106:109], v[90:93]
	s_waitcnt lgkmcnt(3)
	v_pk_mul_f32 v[106:107], v[112:113], v[112:113]
	v_pk_mul_f32 v[108:109], v[110:111], v[110:111]
	s_nop 0
	v_pk_mov_b32 v[114:115], v[108:109], v[106:107] op_sel:[1,0]
	v_mov_b32_e32 v109, v107
	v_pk_add_f32 v[106:107], v[114:115], v[108:109]
	s_waitcnt lgkmcnt(2)
	v_pk_mul_f32 v[108:109], v[104:105], v[104:105]
	v_pk_mul_f32 v[114:115], v[102:103], v[102:103]
	v_pk_add_f32 v[106:107], v[106:107], v[106:107] op_sel:[0,1] op_sel_hi:[1,0]
	v_pk_mov_b32 v[116:117], v[114:115], v[108:109] op_sel:[1,0]
	v_mov_b32_e32 v115, v109
	v_pk_add_f32 v[108:109], v[116:117], v[114:115]
	s_waitcnt lgkmcnt(0)
	v_mul_f32_e32 v114, v94, v94
	v_mul_f32_e32 v115, v95, v95
	v_pk_add_f32 v[108:109], v[108:109], v[108:109] op_sel:[0,1] op_sel_hi:[1,0]
	v_mov_b32_e32 v107, v114
	v_mov_b32_e32 v109, v115
	v_pk_add_f32 v[106:107], v[106:107], v[108:109]
	v_mul_f32_e32 v108, v99, v99
	v_mul_f32_e32 v114, v101, v101
	v_mul_f32_e32 v116, v96, v96
	v_mul_f32_e32 v117, v97, v97
	v_pk_fma_f32 v[108:109], v[98:99], v[98:99], v[108:109] op_sel_hi:[1,1,0]
	v_pk_fma_f32 v[114:115], v[100:101], v[100:101], v[114:115] op_sel_hi:[1,1,0]
	v_mov_b32_e32 v109, v116
	v_mov_b32_e32 v115, v117
	v_pk_add_f32 v[108:109], v[108:109], v[114:115]
	v_mfma_f32_16x16x32_bf16 v[86:89], v[170:173], v[144:147], v[86:89]
	v_add_f32_e64 v106, v106, v108
	v_add_f32_e64 v107, v107, v109
	v_and_b32_e32 v108, 64, v235
	v_add_f32_e32 v106, v106, v107
	v_xor_b32_e32 v107, 1, v235
	v_add_u32_e32 v108, 64, v108
	v_cmp_lt_i32_e32 vcc, v107, v108
	v_mfma_f32_16x16x32_bf16 v[90:93], v[186:189], v[144:147], v[90:93]
	v_and_b32_e32 v146, 0xffff0000, v46
	v_cndmask_b32_e32 v107, v235, v107, vcc
	v_lshlrev_b32_e32 v107, 2, v107
	v_and_b32_e32 v147, 0xffff0000, v47
	v_lshl_add_u64 v[144:145], v[134:135], 0, s[6:7]
	s_waitcnt lgkmcnt(0)
	s_nop 1
	v_add_f32_dpp v106, v106, v106 quad_perm:[1,0,3,2] row_mask:0xf bank_mask:0xf
	v_xor_b32_e32 v107, 2, v235
	v_cmp_lt_i32_e32 vcc, v107, v108
	s_nop 1
	v_cndmask_b32_e32 v107, v235, v107, vcc
	v_lshlrev_b32_e32 v107, 2, v107
	s_waitcnt lgkmcnt(0)
	s_nop 1
	v_add_f32_dpp v106, v106, v106 quad_perm:[2,3,0,1] row_mask:0xf bank_mask:0xf
	v_xor_b32_e32 v107, 4, v235
	v_cmp_lt_i32_e32 vcc, v107, v108
	s_nop 1
	v_cndmask_b32_e32 v107, v235, v107, vcc
	v_lshlrev_b32_e32 v107, 2, v107
	s_waitcnt lgkmcnt(0)
	s_nop 1
	v_add_f32_dpp v106, v106, v106 row_half_mirror row_mask:0xf bank_mask:0xf
	v_fmamk_f32 v106, v106, 0x3c000000, v1
	v_cmp_gt_f32_e32 vcc, s0, v106
	v_mul_f32_e32 v107, 0x4b800000, v106
	s_nop 0
	v_cndmask_b32_e32 v106, v106, v107, vcc
	v_rsq_f32_e32 v106, v106
	s_nop 0
	v_mul_f32_e32 v107, 0x45800000, v106
	v_cndmask_b32_e32 v142, v106, v107, vcc
	v_mul_f32_e32 v106, 0xbfb8aa3b, v150
	v_exp_f32_e32 v106, v106
	v_mov_b32_e32 v107, v112
	v_mov_b32_e32 v112, v111
	v_add_f32_e32 v106, 1.0, v106
	v_rcp_f32_e32 v152, v106
	v_mul_f32_e32 v106, 0xbfb8aa3b, v146
	v_exp_f32_e32 v106, v106
	s_nop 0
	v_add_f32_e32 v106, 1.0, v106
	v_rcp_f32_e32 v148, v106
	v_mov_b32_e32 v106, v110
	v_pk_mul_f32 v[154:155], v[106:107], v[142:143] op_sel_hi:[1,0]
	v_mov_b32_e32 v106, v246
	v_mov_b32_e32 v107, v247
	v_mov_b32_e32 v108, v248
	v_mov_b32_e32 v109, v249
	v_mov_b32_e32 v114, v242
	v_mov_b32_e32 v115, v243
	v_mov_b32_e32 v116, v244
	v_mov_b32_e32 v117, v245
	v_mul_f32_e32 v110, 0xbfb8aa3b, v151
	v_exp_f32_e32 v110, v110
	v_mov_b32_e32 v171, v116
	v_add_f32_e32 v110, 1.0, v110
	v_rcp_f32_e32 v153, v110
	v_pk_mul_f32 v[110:111], v[112:113], v[142:143] op_sel_hi:[1,0]
	v_mul_f32_e32 v112, 0xbfb8aa3b, v147
	v_exp_f32_e32 v112, v112
	v_mov_b32_e32 v116, v115
	v_pk_mul_f32 v[110:111], v[116:117], v[110:111]
	v_mov_b32_e32 v170, v114
	v_add_f32_e32 v112, 1.0, v112
	v_rcp_f32_e32 v149, v112
	v_and_b32_e32 v114, 0xffff0000, v48
	v_mul_f32_e32 v117, 0xbfb8aa3b, v114
	v_exp_f32_e32 v117, v117
	v_pk_mul_f32 v[112:113], v[148:149], v[146:147]
	v_mov_b32_e32 v148, v102
	v_pk_mul_f32 v[110:111], v[112:113], v[110:111]
	v_lshlrev_b32_e32 v113, 16, v49
	v_mul_f32_e32 v102, 0xbfb8aa3b, v113
	v_exp_f32_e32 v102, v102
	v_and_b32_e32 v115, 0xffff0000, v49
	v_add_f32_e32 v117, 1.0, v117
	v_mov_b32_e32 v149, v104
	v_add_f32_e32 v102, 1.0, v102
	v_mov_b32_e32 v104, v103
	v_lshlrev_b32_e32 v112, 16, v48
	v_rcp_f32_e32 v146, v117
	v_rcp_f32_e32 v117, v102
	v_pk_mul_f32 v[102:103], v[104:105], v[142:143] op_sel_hi:[1,0]
	v_mul_f32_e32 v104, 0xbfb8aa3b, v115
	v_mul_f32_e32 v116, 0xbfb8aa3b, v112
	v_exp_f32_e32 v104, v104
	v_exp_f32_e32 v116, v116
	v_pk_mul_f32 v[150:151], v[152:153], v[150:151]
	v_mov_b32_e32 v153, v108
	v_add_f32_e32 v104, 1.0, v104
	v_add_f32_e32 v116, 1.0, v116
	v_rcp_f32_e32 v147, v104
	v_rcp_f32_e32 v116, v116
	v_mov_b32_e32 v108, v107
	v_pk_mul_f32 v[148:149], v[148:149], v[142:143] op_sel_hi:[1,0]
	v_mov_b32_e32 v152, v106
	v_pk_mul_f32 v[102:103], v[108:109], v[102:103]
	v_pk_mul_f32 v[104:105], v[146:147], v[114:115]
	v_pk_mul_f32 v[154:155], v[170:171], v[154:155]
	v_pk_mul_f32 v[148:149], v[152:153], v[148:149]
	v_pk_mul_f32 v[112:113], v[116:117], v[112:113]
	v_pk_mul_f32 v[102:103], v[104:105], v[102:103]
	v_pk_mul_f32 v[150:151], v[150:151], v[154:155]
	v_pk_mul_f32 v[112:113], v[112:113], v[148:149]
	v_bfe_u32 v105, v102, 16, 1
	v_bfe_u32 v104, v103, 16, 1
	v_add3_u32 v102, v102, v105, s33
	v_bfe_u32 v105, v151, 16, 1
	v_bfe_u32 v109, v113, 16, 1
	v_bfe_u32 v106, v111, 16, 1
	v_add3_u32 v103, v103, v104, s33
	v_bfe_u32 v104, v150, 16, 1
	v_bfe_u32 v108, v112, 16, 1
	v_add3_u32 v109, v113, v109, s33
	v_add3_u32 v105, v151, v105, s33
	v_bfe_u32 v107, v110, 16, 1
	v_add3_u32 v106, v111, v106, s33
	v_add3_u32 v108, v112, v108, s33
	v_add3_u32 v104, v150, v104, s33
	v_lshrrev_b32_e32 v111, 16, v105
	v_lshrrev_b32_e32 v105, 16, v109
	v_add3_u32 v107, v110, v107, s33
	v_lshrrev_b32_e32 v110, 16, v104
	v_lshrrev_b32_e32 v104, 16, v108
	v_and_or_b32 v105, v103, s21, v105
	v_and_or_b32 v103, v106, s21, v111
	v_add_co_u32_e32 v106, vcc, s30, v144
	v_and_or_b32 v104, v102, s21, v104
	v_and_or_b32 v102, v107, s21, v110
	v_addc_co_u32_e32 v107, vcc, 0, v145, vcc
	v_lshlrev_b32_e32 v114, 16, v50
	global_store_dwordx4 v[106:107], v[102:105], off offset:1024
	v_and_b32_e32 v108, 0xffff0000, v50
	v_lshlrev_b32_e32 v115, 16, v51
	v_mul_f32_e32 v102, 0xbfb8aa3b, v114
	v_exp_f32_e32 v102, v102
	v_mov_b32_e32 v103, v100
	v_and_b32_e32 v109, 0xffff0000, v51
	v_mov_b32_e32 v100, v99
	v_add_f32_e32 v102, 1.0, v102
	v_rcp_f32_e32 v116, v102
	v_mul_f32_e32 v102, 0xbfb8aa3b, v108
	v_exp_f32_e32 v102, v102
	s_andn2_b64 vcc, exec, s[8:9]
	v_add_f32_e32 v102, 1.0, v102
	v_rcp_f32_e32 v144, v102
	v_mov_b32_e32 v102, v98
	v_pk_mul_f32 v[146:147], v[102:103], v[142:143] op_sel_hi:[1,0]
	v_mov_b32_e32 v102, v230
	v_mov_b32_e32 v103, v234
	v_mov_b32_e32 v104, v236
	v_mov_b32_e32 v105, v238
	v_mov_b32_e32 v110, v250
	v_mov_b32_e32 v111, v251
	v_mov_b32_e32 v112, v241
	v_mov_b32_e32 v113, v228
	v_mul_f32_e32 v98, 0xbfb8aa3b, v115
	v_exp_f32_e32 v98, v98
	v_mov_b32_e32 v149, v112
	v_add_f32_e32 v98, 1.0, v98
	v_rcp_f32_e32 v117, v98
	v_pk_mul_f32 v[98:99], v[100:101], v[142:143] op_sel_hi:[1,0]
	v_mul_f32_e32 v100, 0xbfb8aa3b, v109
	v_exp_f32_e32 v100, v100
	v_mov_b32_e32 v112, v111
	v_pk_mul_f32 v[98:99], v[112:113], v[98:99]
	v_pk_mul_f32 v[114:115], v[116:117], v[114:115]
	v_add_f32_e32 v100, 1.0, v100
	v_rcp_f32_e32 v145, v100
	v_mov_b32_e32 v116, v94
	v_mov_b32_e32 v117, v96
	v_mov_b32_e32 v96, v95
	v_pk_mul_f32 v[100:101], v[144:145], v[108:109]
	v_and_b32_e32 v108, 0xffff0000, v52
	v_pk_mul_f32 v[98:99], v[100:101], v[98:99]
	v_lshlrev_b32_e32 v101, 16, v53
	v_mul_f32_e32 v111, 0xbfb8aa3b, v108
	v_mul_f32_e32 v94, 0xbfb8aa3b, v101
	v_exp_f32_e32 v111, v111
	v_exp_f32_e32 v94, v94
	v_and_b32_e32 v109, 0xffff0000, v53
	v_lshlrev_b32_e32 v100, 16, v52
	v_add_f32_e32 v111, 1.0, v111
	v_add_f32_e32 v94, 1.0, v94
	v_rcp_f32_e32 v112, v111
	v_rcp_f32_e32 v111, v94
	v_pk_mul_f32 v[94:95], v[96:97], v[142:143] op_sel_hi:[1,0]
	v_mul_f32_e32 v96, 0xbfb8aa3b, v109
	v_mov_b32_e32 v148, v110
	v_mul_f32_e32 v110, 0xbfb8aa3b, v100
	v_exp_f32_e32 v96, v96
	v_exp_f32_e32 v110, v110
	v_mov_b32_e32 v145, v104
	v_mov_b32_e32 v104, v103
	v_add_f32_e32 v96, 1.0, v96
	v_add_f32_e32 v110, 1.0, v110
	v_rcp_f32_e32 v113, v96
	v_rcp_f32_e32 v110, v110
	v_pk_mul_f32 v[116:117], v[116:117], v[142:143] op_sel_hi:[1,0]
	v_mov_b32_e32 v144, v102
	v_pk_mul_f32 v[94:95], v[94:95], v[104:105]
	v_pk_mul_f32 v[96:97], v[112:113], v[108:109]
	v_pk_mul_f32 v[146:147], v[148:149], v[146:147]
	v_pk_mul_f32 v[116:117], v[116:117], v[144:145]
	v_pk_mul_f32 v[100:101], v[110:111], v[100:101]
	v_pk_mul_f32 v[94:95], v[96:97], v[94:95]
	v_pk_mul_f32 v[114:115], v[114:115], v[146:147]
	v_pk_mul_f32 v[100:101], v[100:101], v[116:117]
	v_bfe_u32 v96, v95, 16, 1
	v_bfe_u32 v97, v94, 16, 1
	v_bfe_u32 v102, v99, 16, 1
	v_bfe_u32 v103, v98, 16, 1
	v_add3_u32 v98, v98, v103, s33
	v_add3_u32 v99, v99, v102, s33
	v_add3_u32 v94, v94, v97, s33
	v_add3_u32 v95, v95, v96, s33
	v_bfe_u32 v96, v114, 16, 1
	v_bfe_u32 v97, v115, 16, 1
	v_bfe_u32 v102, v100, 16, 1
	v_bfe_u32 v103, v101, 16, 1
	v_add3_u32 v101, v101, v103, s33
	v_add3_u32 v100, v100, v102, s33
	v_add3_u32 v97, v115, v97, s33
	v_add3_u32 v96, v114, v96, s33
	v_lshrrev_b32_e32 v102, 16, v96
	v_lshrrev_b32_e32 v103, 16, v97
	v_lshrrev_b32_e32 v96, 16, v100
	v_lshrrev_b32_e32 v97, 16, v101
	v_and_or_b32 v97, v95, s21, v97
	v_and_or_b32 v96, v94, s21, v96
	v_and_or_b32 v95, v99, s21, v103
	v_and_or_b32 v94, v98, s21, v102
	global_store_dwordx4 v[106:107], v[94:97], off offset:1040
	s_cbranch_vccnz .LBB0_444
	s_waitcnt vmcnt(2)
	v_mov_b64_e32 v[46:47], v[58:59]
	v_mov_b64_e32 v[50:51], v[54:55]
	v_mov_b64_e32 v[48:49], v[60:61]
	v_mov_b64_e32 v[52:53], v[56:57]
	v_mov_b32_e32 v130, v162
	ds_write_b128 v119, v[2:5]
	ds_write_b128 v156, v[6:9]
	ds_write_b128 v119, v[10:13] offset:17408
	ds_write_b128 v156, v[14:17] offset:17408
	ds_write_b128 v143, v[18:21] offset:34816
	ds_write_b128 v143, v[22:25] offset:44032
	ds_write_b128 v157, v[26:29] offset:44032
	ds_write_b128 v158, v[30:33]
	ds_write_b128 v159, v[34:37]
	ds_write_b128 v160, v[38:41]
	ds_write_b128 v161, v[42:45]
	s_branch .LBB0_444
